# P2 rebalanced (split arrive/wait for 3-tile GEMM workgroups, kn_items after the P2-P3 barrier); SWA units now 1 per recurrence / 3-tile workgroup and 3 per 2-tile workgroup
# speedup vs baseline: 1.0066x; 1.0030x over previous
; __device__ __forceinline__ void swa_units(Frame& F, int u0, int stride) {
;     if (u0 >= 512) return;
;     u32x4 kt_[4], vt_[4];
;     __syncthreads();
;     swa_load(F, u0, kt_, vt_);
;     swa_stage(F, kt_, vt_);
;     __syncthreads();
;     for (int u = u0;;) {
;         const int un = u + stride; const bool has = un < 512;
;         if (has) swa_load(F, un, kt_, vt_);
;         swa_compute(F, u);
;         if (!has) break;
;         __syncthreads();
;         swa_stage(F, kt_, vt_);
;         __syncthreads();
;         u = un;
.LBB0_583:
	s_mov_b32 s101, s2
	s_mov_b32 s100, s33
	s_movk_i32 s99, 0x200
	s_cmpk_eq_i32 s33, 0x100
	s_cbranch_scc0 .Lswa_cfg
	s_movk_i32 s100, 0x80
	s_cmp_gt_i32 s2, 0x7f
	s_cbranch_scc1 .Lswa_cfg
	s_movk_i32 s99, 0x80
